# final RMSNorm routines: y stores without the non-temporal hint (loads keep it)
# baseline (speedup 1.0000x reference)
.Lp10a_loop:
	s_add_u32 s8, s12, 0x1000
	s_addc_u32 s9, s13, 0
	global_load_dwordx2 v[20:21], v1, s[12:13] nt
	global_load_dwordx2 v[22:23], v1, s[12:13] offset:512 nt
	global_load_dwordx2 v[24:25], v1, s[12:13] offset:1024 nt
	global_load_dwordx2 v[26:27], v1, s[12:13] offset:1536 nt
	global_load_dwordx2 v[28:29], v1, s[12:13] offset:2048 nt
	global_load_dwordx2 v[30:31], v1, s[12:13] offset:2560 nt
	global_load_dwordx2 v[32:33], v1, s[12:13] offset:3072 nt
	global_load_dwordx2 v[34:35], v1, s[12:13] offset:3584 nt
	global_load_dwordx2 v[36:37], v1, s[8:9] nt
	global_load_dwordx2 v[38:39], v1, s[8:9] offset:512 nt
	global_load_dwordx2 v[40:41], v1, s[8:9] offset:1024 nt
	global_load_dwordx2 v[42:43], v1, s[8:9] offset:1536 nt
	global_load_dwordx2 v[44:45], v1, s[8:9] offset:2048 nt
	global_load_dwordx2 v[46:47], v1, s[8:9] offset:2560 nt
	global_load_dwordx2 v[48:49], v1, s[8:9] offset:3072 nt
	global_load_dwordx2 v[50:51], v1, s[8:9] offset:3584 nt
	s_waitcnt vmcnt(0)
	v_lshlrev_b32_e32 v52, 16, v20
	v_and_b32_e32 v53, 0xffff0000, v20
	v_lshlrev_b32_e32 v54, 16, v21
	v_and_b32_e32 v55, 0xffff0000, v21
	v_lshlrev_b32_e32 v56, 16, v22
	v_and_b32_e32 v57, 0xffff0000, v22
	v_lshlrev_b32_e32 v58, 16, v23
	v_and_b32_e32 v59, 0xffff0000, v23
	v_lshlrev_b32_e32 v60, 16, v24
	v_and_b32_e32 v61, 0xffff0000, v24
	v_lshlrev_b32_e32 v62, 16, v25
	v_and_b32_e32 v63, 0xffff0000, v25
	v_lshlrev_b32_e32 v64, 16, v26
	v_and_b32_e32 v65, 0xffff0000, v26
	v_lshlrev_b32_e32 v66, 16, v27
	v_and_b32_e32 v67, 0xffff0000, v27
	v_lshlrev_b32_e32 v68, 16, v28
	v_and_b32_e32 v69, 0xffff0000, v28
	v_lshlrev_b32_e32 v70, 16, v29
	v_and_b32_e32 v71, 0xffff0000, v29
	v_lshlrev_b32_e32 v72, 16, v30
	v_and_b32_e32 v73, 0xffff0000, v30
	v_lshlrev_b32_e32 v74, 16, v31
	v_and_b32_e32 v75, 0xffff0000, v31
	v_lshlrev_b32_e32 v76, 16, v32
	v_and_b32_e32 v77, 0xffff0000, v32
	v_lshlrev_b32_e32 v78, 16, v33
	v_and_b32_e32 v79, 0xffff0000, v33
	v_lshlrev_b32_e32 v80, 16, v34
	v_and_b32_e32 v81, 0xffff0000, v34
	v_lshlrev_b32_e32 v82, 16, v35
	v_and_b32_e32 v83, 0xffff0000, v35
	v_lshlrev_b32_e32 v84, 16, v36
	v_and_b32_e32 v85, 0xffff0000, v36
	v_lshlrev_b32_e32 v86, 16, v37
	v_and_b32_e32 v87, 0xffff0000, v37
	v_lshlrev_b32_e32 v88, 16, v38
	v_and_b32_e32 v89, 0xffff0000, v38
	v_lshlrev_b32_e32 v90, 16, v39
	v_and_b32_e32 v91, 0xffff0000, v39
	v_lshlrev_b32_e32 v92, 16, v40
	v_and_b32_e32 v93, 0xffff0000, v40
	v_lshlrev_b32_e32 v94, 16, v41
	v_and_b32_e32 v95, 0xffff0000, v41
	v_lshlrev_b32_e32 v96, 16, v42
	v_and_b32_e32 v97, 0xffff0000, v42
	v_lshlrev_b32_e32 v98, 16, v43
	v_and_b32_e32 v99, 0xffff0000, v43
	v_lshlrev_b32_e32 v100, 16, v44
	v_and_b32_e32 v101, 0xffff0000, v44
	v_lshlrev_b32_e32 v102, 16, v45
	v_and_b32_e32 v103, 0xffff0000, v45
	v_lshlrev_b32_e32 v104, 16, v46
	v_and_b32_e32 v105, 0xffff0000, v46
	v_lshlrev_b32_e32 v106, 16, v47
	v_and_b32_e32 v107, 0xffff0000, v47
	v_lshlrev_b32_e32 v108, 16, v48
	v_and_b32_e32 v109, 0xffff0000, v48
	v_lshlrev_b32_e32 v110, 16, v49
	v_and_b32_e32 v111, 0xffff0000, v49
	v_lshlrev_b32_e32 v112, 16, v50
	v_and_b32_e32 v113, 0xffff0000, v50
	v_lshlrev_b32_e32 v114, 16, v51
	v_and_b32_e32 v115, 0xffff0000, v51
	v_mul_f32_e32 v116, v52, v52
	v_mul_f32_e32 v117, v68, v68
	v_mul_f32_e32 v118, v84, v84
	v_mul_f32_e32 v119, v100, v100
	v_fmac_f32_e32 v116, v53, v53
	v_fmac_f32_e32 v117, v69, v69
	v_fmac_f32_e32 v118, v85, v85
	v_fmac_f32_e32 v119, v101, v101
	v_fmac_f32_e32 v116, v54, v54
	v_fmac_f32_e32 v117, v70, v70
	v_fmac_f32_e32 v118, v86, v86
	v_fmac_f32_e32 v119, v102, v102
	v_fmac_f32_e32 v116, v55, v55
	v_fmac_f32_e32 v117, v71, v71
	v_fmac_f32_e32 v118, v87, v87
	v_fmac_f32_e32 v119, v103, v103
	v_fmac_f32_e32 v116, v56, v56
	v_fmac_f32_e32 v117, v72, v72
	v_fmac_f32_e32 v118, v88, v88
	v_fmac_f32_e32 v119, v104, v104
	v_fmac_f32_e32 v116, v57, v57
	v_fmac_f32_e32 v117, v73, v73
	v_fmac_f32_e32 v118, v89, v89
	v_fmac_f32_e32 v119, v105, v105
	v_fmac_f32_e32 v116, v58, v58
	v_fmac_f32_e32 v117, v74, v74
	v_fmac_f32_e32 v118, v90, v90
	v_fmac_f32_e32 v119, v106, v106
	v_fmac_f32_e32 v116, v59, v59
	v_fmac_f32_e32 v117, v75, v75
	v_fmac_f32_e32 v118, v91, v91
	v_fmac_f32_e32 v119, v107, v107
	v_fmac_f32_e32 v116, v60, v60
	v_fmac_f32_e32 v117, v76, v76
	v_fmac_f32_e32 v118, v92, v92
	v_fmac_f32_e32 v119, v108, v108
	v_fmac_f32_e32 v116, v61, v61
	v_fmac_f32_e32 v117, v77, v77
	v_fmac_f32_e32 v118, v93, v93
	v_fmac_f32_e32 v119, v109, v109
	v_fmac_f32_e32 v116, v62, v62
	v_fmac_f32_e32 v117, v78, v78
	v_fmac_f32_e32 v118, v94, v94
	v_fmac_f32_e32 v119, v110, v110
	v_fmac_f32_e32 v116, v63, v63
	v_fmac_f32_e32 v117, v79, v79
	v_fmac_f32_e32 v118, v95, v95
	v_fmac_f32_e32 v119, v111, v111
	v_fmac_f32_e32 v116, v64, v64
	v_fmac_f32_e32 v117, v80, v80
	v_fmac_f32_e32 v118, v96, v96
	v_fmac_f32_e32 v119, v112, v112
	v_fmac_f32_e32 v116, v65, v65
	v_fmac_f32_e32 v117, v81, v81
	v_fmac_f32_e32 v118, v97, v97
	v_fmac_f32_e32 v119, v113, v113
	v_fmac_f32_e32 v116, v66, v66
	v_fmac_f32_e32 v117, v82, v82
	v_fmac_f32_e32 v118, v98, v98
	v_fmac_f32_e32 v119, v114, v114
	v_fmac_f32_e32 v116, v67, v67
	v_fmac_f32_e32 v117, v83, v83
	v_fmac_f32_e32 v118, v99, v99
	v_fmac_f32_e32 v119, v115, v115
	v_add_f32_dpp v132, v116, v116 quad_perm:[1,0,3,2] row_mask:0xf bank_mask:0xf
	v_add_f32_dpp v133, v117, v117 quad_perm:[1,0,3,2] row_mask:0xf bank_mask:0xf
	v_add_f32_dpp v134, v118, v118 quad_perm:[1,0,3,2] row_mask:0xf bank_mask:0xf
	v_add_f32_dpp v135, v119, v119 quad_perm:[1,0,3,2] row_mask:0xf bank_mask:0xf
	v_add_f32_dpp v136, v132, v132 quad_perm:[2,3,0,1] row_mask:0xf bank_mask:0xf
	v_add_f32_dpp v137, v133, v133 quad_perm:[2,3,0,1] row_mask:0xf bank_mask:0xf
	v_add_f32_dpp v138, v134, v134 quad_perm:[2,3,0,1] row_mask:0xf bank_mask:0xf
	v_add_f32_dpp v139, v135, v135 quad_perm:[2,3,0,1] row_mask:0xf bank_mask:0xf
	v_add_f32_dpp v132, v136, v136 row_ror:4 row_mask:0xf bank_mask:0xf
	v_add_f32_dpp v133, v137, v137 row_ror:4 row_mask:0xf bank_mask:0xf
	v_add_f32_dpp v134, v138, v138 row_ror:4 row_mask:0xf bank_mask:0xf
	v_add_f32_dpp v135, v139, v139 row_ror:4 row_mask:0xf bank_mask:0xf
	v_add_f32_dpp v136, v132, v132 row_ror:8 row_mask:0xf bank_mask:0xf
	v_add_f32_dpp v137, v133, v133 row_ror:8 row_mask:0xf bank_mask:0xf
	v_add_f32_dpp v138, v134, v134 row_ror:8 row_mask:0xf bank_mask:0xf
	v_add_f32_dpp v139, v135, v135 row_ror:8 row_mask:0xf bank_mask:0xf
	s_nop 1
	v_readlane_b32 s16, v136, 0
	v_readlane_b32 s17, v136, 16
	v_readlane_b32 s18, v136, 32
	v_readlane_b32 s19, v136, 48
	v_readlane_b32 s20, v137, 0
	v_readlane_b32 s21, v137, 16
	v_readlane_b32 s22, v137, 32
	v_readlane_b32 s23, v137, 48
	v_readlane_b32 s24, v138, 0
	v_readlane_b32 s25, v138, 16
	v_readlane_b32 s26, v138, 32
	v_readlane_b32 s27, v138, 48
	v_readlane_b32 s28, v139, 0
	v_readlane_b32 s29, v139, 16
	v_readlane_b32 s30, v139, 32
	v_readlane_b32 s31, v139, 48
	s_nop 1
	v_mov_b32_e32 v132, s16
	v_mov_b32_e32 v133, s20
	v_mov_b32_e32 v134, s24
	v_mov_b32_e32 v135, s28
	v_add_f32_e32 v132, s17, v132
	v_add_f32_e32 v133, s21, v133
	v_add_f32_e32 v134, s25, v134
	v_add_f32_e32 v135, s29, v135
	v_add_f32_e32 v132, s18, v132
	v_add_f32_e32 v133, s22, v133
	v_add_f32_e32 v134, s26, v134
	v_add_f32_e32 v135, s30, v135
	v_add_f32_e32 v132, s19, v132
	v_add_f32_e32 v133, s23, v133
	v_add_f32_e32 v134, s27, v134
	v_add_f32_e32 v135, s31, v135
	v_fma_f32 v140, v132, v3, v121
	v_fma_f32 v141, v133, v3, v121
	v_fma_f32 v142, v134, v3, v121
	v_fma_f32 v143, v135, v3, v121
	v_rsq_f32_e32 v124, v140
	v_rsq_f32_e32 v126, v141
	v_rsq_f32_e32 v128, v142
	v_rsq_f32_e32 v130, v143
	s_nop 0
	v_mul_f32_e32 v132, v140, v124
	v_mul_f32_e32 v133, v141, v126
	v_mul_f32_e32 v134, v142, v128
	v_mul_f32_e32 v135, v143, v130
	v_mul_f32_e32 v132, v132, v124
	v_mul_f32_e32 v133, v133, v126
	v_mul_f32_e32 v134, v134, v128
	v_mul_f32_e32 v135, v135, v130
	v_sub_f32_e32 v132, 1.0, v132
	v_sub_f32_e32 v133, 1.0, v133
	v_sub_f32_e32 v134, 1.0, v134
	v_sub_f32_e32 v135, 1.0, v135
	v_mul_f32_e32 v136, 0.5, v124
	v_mul_f32_e32 v137, 0.5, v126
	v_mul_f32_e32 v138, 0.5, v128
	v_mul_f32_e32 v139, 0.5, v130
	v_fmac_f32_e32 v124, v136, v132
	v_fmac_f32_e32 v126, v137, v133
	v_fmac_f32_e32 v128, v138, v134
	v_fmac_f32_e32 v130, v139, v135
	v_pk_mul_f32 v[52:53], v[52:53], v[124:125] op_sel_hi:[1,0]
	v_pk_mul_f32 v[54:55], v[54:55], v[124:125] op_sel_hi:[1,0]
	v_pk_mul_f32 v[56:57], v[56:57], v[124:125] op_sel_hi:[1,0]
	v_pk_mul_f32 v[58:59], v[58:59], v[124:125] op_sel_hi:[1,0]
	v_pk_mul_f32 v[60:61], v[60:61], v[124:125] op_sel_hi:[1,0]
	v_pk_mul_f32 v[62:63], v[62:63], v[124:125] op_sel_hi:[1,0]
	v_pk_mul_f32 v[64:65], v[64:65], v[124:125] op_sel_hi:[1,0]
	v_pk_mul_f32 v[66:67], v[66:67], v[124:125] op_sel_hi:[1,0]
	v_pk_mul_f32 v[52:53], v[52:53], v[4:5]
	v_pk_mul_f32 v[54:55], v[54:55], v[6:7]
	v_pk_mul_f32 v[56:57], v[56:57], v[8:9]
	v_pk_mul_f32 v[58:59], v[58:59], v[10:11]
	v_pk_mul_f32 v[60:61], v[60:61], v[12:13]
	v_pk_mul_f32 v[62:63], v[62:63], v[14:15]
	v_pk_mul_f32 v[64:65], v[64:65], v[16:17]
	v_pk_mul_f32 v[66:67], v[66:67], v[18:19]
	global_store_dwordx4 v2, v[52:55], s[14:15]
	global_store_dwordx4 v2, v[56:59], s[14:15] offset:1024
	global_store_dwordx4 v2, v[60:63], s[14:15] offset:2048
	global_store_dwordx4 v2, v[64:67], s[14:15] offset:3072
	v_pk_mul_f32 v[68:69], v[68:69], v[126:127] op_sel_hi:[1,0]
	v_pk_mul_f32 v[70:71], v[70:71], v[126:127] op_sel_hi:[1,0]
	v_pk_mul_f32 v[72:73], v[72:73], v[126:127] op_sel_hi:[1,0]
	v_pk_mul_f32 v[74:75], v[74:75], v[126:127] op_sel_hi:[1,0]
	v_pk_mul_f32 v[76:77], v[76:77], v[126:127] op_sel_hi:[1,0]
	v_pk_mul_f32 v[78:79], v[78:79], v[126:127] op_sel_hi:[1,0]
	v_pk_mul_f32 v[80:81], v[80:81], v[126:127] op_sel_hi:[1,0]
	v_pk_mul_f32 v[82:83], v[82:83], v[126:127] op_sel_hi:[1,0]
	v_pk_mul_f32 v[68:69], v[68:69], v[4:5]
	v_pk_mul_f32 v[70:71], v[70:71], v[6:7]
	v_pk_mul_f32 v[72:73], v[72:73], v[8:9]
	v_pk_mul_f32 v[74:75], v[74:75], v[10:11]
	v_pk_mul_f32 v[76:77], v[76:77], v[12:13]
	v_pk_mul_f32 v[78:79], v[78:79], v[14:15]
	v_pk_mul_f32 v[80:81], v[80:81], v[16:17]
	v_pk_mul_f32 v[82:83], v[82:83], v[18:19]
	s_add_u32 s2, s14, 0x1000
	s_addc_u32 s3, s15, 0
	global_store_dwordx4 v2, v[68:71], s[2:3]
	global_store_dwordx4 v2, v[72:75], s[2:3] offset:1024
	global_store_dwordx4 v2, v[76:79], s[2:3] offset:2048
	global_store_dwordx4 v2, v[80:83], s[2:3] offset:3072
	v_pk_mul_f32 v[84:85], v[84:85], v[128:129] op_sel_hi:[1,0]
	v_pk_mul_f32 v[86:87], v[86:87], v[128:129] op_sel_hi:[1,0]
	v_pk_mul_f32 v[88:89], v[88:89], v[128:129] op_sel_hi:[1,0]
	v_pk_mul_f32 v[90:91], v[90:91], v[128:129] op_sel_hi:[1,0]
	v_pk_mul_f32 v[92:93], v[92:93], v[128:129] op_sel_hi:[1,0]
	v_pk_mul_f32 v[94:95], v[94:95], v[128:129] op_sel_hi:[1,0]
	v_pk_mul_f32 v[96:97], v[96:97], v[128:129] op_sel_hi:[1,0]
	v_pk_mul_f32 v[98:99], v[98:99], v[128:129] op_sel_hi:[1,0]
	v_pk_mul_f32 v[84:85], v[84:85], v[4:5]
	v_pk_mul_f32 v[86:87], v[86:87], v[6:7]
	v_pk_mul_f32 v[88:89], v[88:89], v[8:9]
	v_pk_mul_f32 v[90:91], v[90:91], v[10:11]
	v_pk_mul_f32 v[92:93], v[92:93], v[12:13]
	v_pk_mul_f32 v[94:95], v[94:95], v[14:15]
	v_pk_mul_f32 v[96:97], v[96:97], v[16:17]
	v_pk_mul_f32 v[98:99], v[98:99], v[18:19]
	s_add_u32 s2, s14, 0x2000
	s_addc_u32 s3, s15, 0
	global_store_dwordx4 v2, v[84:87], s[2:3]
	global_store_dwordx4 v2, v[88:91], s[2:3] offset:1024
	global_store_dwordx4 v2, v[92:95], s[2:3] offset:2048
	global_store_dwordx4 v2, v[96:99], s[2:3] offset:3072
	v_pk_mul_f32 v[100:101], v[100:101], v[130:131] op_sel_hi:[1,0]
	v_pk_mul_f32 v[102:103], v[102:103], v[130:131] op_sel_hi:[1,0]
	v_pk_mul_f32 v[104:105], v[104:105], v[130:131] op_sel_hi:[1,0]
	v_pk_mul_f32 v[106:107], v[106:107], v[130:131] op_sel_hi:[1,0]
	v_pk_mul_f32 v[108:109], v[108:109], v[130:131] op_sel_hi:[1,0]
	v_pk_mul_f32 v[110:111], v[110:111], v[130:131] op_sel_hi:[1,0]
	v_pk_mul_f32 v[112:113], v[112:113], v[130:131] op_sel_hi:[1,0]
	v_pk_mul_f32 v[114:115], v[114:115], v[130:131] op_sel_hi:[1,0]
	v_pk_mul_f32 v[100:101], v[100:101], v[4:5]
	v_pk_mul_f32 v[102:103], v[102:103], v[6:7]
	v_pk_mul_f32 v[104:105], v[104:105], v[8:9]
	v_pk_mul_f32 v[106:107], v[106:107], v[10:11]
	v_pk_mul_f32 v[108:109], v[108:109], v[12:13]
	v_pk_mul_f32 v[110:111], v[110:111], v[14:15]
	v_pk_mul_f32 v[112:113], v[112:113], v[16:17]
	v_pk_mul_f32 v[114:115], v[114:115], v[18:19]
	s_add_u32 s2, s14, 0x3000
	s_addc_u32 s3, s15, 0
	global_store_dwordx4 v2, v[100:103], s[2:3]
	global_store_dwordx4 v2, v[104:107], s[2:3] offset:1024
	global_store_dwordx4 v2, v[108:111], s[2:3] offset:2048
	global_store_dwordx4 v2, v[112:115], s[2:3] offset:3072
	s_add_u32 s12, s12, 0x2000
	s_addc_u32 s13, s13, 0
	s_add_u32 s14, s14, 0x4000
	s_addc_u32 s15, s15, 0
	s_add_i32 s10, s10, -1
	s_cmp_lg_u32 s10, 0
	s_cbranch_scc1 .Lp10a_loop
